# ssd_state and ssd_out: wave-0 chunk scan via DPP instead of 12 dependent ds_bpermute
# speedup vs baseline: 1.0017x; 1.0017x over previous
.LBB0_310:
	v_readlane_b32 s36, v253, 39
	v_readlane_b32 s37, v253, 40
	s_and_b64 vcc, exec, s[36:37]
	s_cbranch_vccnz .LBB0_312
	v_mul_f32_e32 v24, v88, v41
	v_mul_f32_e32 v25, v89, v43
	v_fmac_f32_e32 v24, v88, v40
	v_fmac_f32_e32 v25, v89, v42
	v_mov_b32_e32 v26, v25
	s_nop 0
	v_add_f32_dpp v24, v24, v24 row_shr:1 row_mask:0xf bank_mask:0xf
	v_add_f32_dpp v25, v25, v25 row_shr:1 row_mask:0xf bank_mask:0xf
	s_nop 0
	v_add_f32_dpp v24, v24, v24 row_shr:2 row_mask:0xf bank_mask:0xf
	v_add_f32_dpp v25, v25, v25 row_shr:2 row_mask:0xf bank_mask:0xf
	s_nop 0
	v_add_f32_dpp v24, v24, v24 row_shr:4 row_mask:0xf bank_mask:0xf
	v_add_f32_dpp v25, v25, v25 row_shr:4 row_mask:0xf bank_mask:0xf
	s_nop 0
	v_add_f32_dpp v24, v24, v24 row_shr:8 row_mask:0xf bank_mask:0xf
	v_add_f32_dpp v25, v25, v25 row_shr:8 row_mask:0xf bank_mask:0xf
	s_nop 0
	v_add_f32_dpp v24, v24, v24 row_bcast:15 row_mask:0xa bank_mask:0xf
	v_add_f32_dpp v25, v25, v25 row_bcast:15 row_mask:0xa bank_mask:0xf
	s_nop 0
	v_add_f32_dpp v24, v24, v24 row_bcast:31 row_mask:0xc bank_mask:0xf
	v_add_f32_dpp v25, v25, v25 row_bcast:31 row_mask:0xc bank_mask:0xf
	s_nop 0
	v_readlane_b32 s98, v25, 63
	s_nop 1
	v_sub_f32_e32 v27, s98, v25
	v_add_f32_e32 v26, v27, v26
	v_fma_f32 v27, -v89, v42, v26
	v_mov_b32_e32 v25, v24
	v_fma_f32 v24, -v88, v41, v25
	ds_write2st64_b64 v87, v[24:25], v[26:27] offset1:1
	ds_write2st64_b64 v87, v[40:41], v[42:43] offset0:2 offset1:3

.LBB0_440:
	v_readlane_b32 s0, v253, 39
	s_lshl_b32 s68, s70, 11
	v_readlane_b32 s1, v253, 40
	s_mov_b32 s6, s91
	s_and_b64 vcc, exec, s[0:1]
	s_add_i32 s91, s68, 0
	s_cbranch_vccnz .LBB0_442
	v_mul_f32_e32 v104, v178, v141
	v_mul_f32_e32 v105, v182, v143
	v_fmac_f32_e32 v104, v178, v140
	v_fmac_f32_e32 v105, v182, v142
	v_lshl_add_u32 v108, v162, 2, s91
	v_mov_b32_e32 v106, v105
	s_nop 0
	v_add_f32_dpp v104, v104, v104 row_shr:1 row_mask:0xf bank_mask:0xf
	v_add_f32_dpp v105, v105, v105 row_shr:1 row_mask:0xf bank_mask:0xf
	s_nop 0
	v_add_f32_dpp v104, v104, v104 row_shr:2 row_mask:0xf bank_mask:0xf
	v_add_f32_dpp v105, v105, v105 row_shr:2 row_mask:0xf bank_mask:0xf
	s_nop 0
	v_add_f32_dpp v104, v104, v104 row_shr:4 row_mask:0xf bank_mask:0xf
	v_add_f32_dpp v105, v105, v105 row_shr:4 row_mask:0xf bank_mask:0xf
	s_nop 0
	v_add_f32_dpp v104, v104, v104 row_shr:8 row_mask:0xf bank_mask:0xf
	v_add_f32_dpp v105, v105, v105 row_shr:8 row_mask:0xf bank_mask:0xf
	s_nop 0
	v_add_f32_dpp v104, v104, v104 row_bcast:15 row_mask:0xa bank_mask:0xf
	v_add_f32_dpp v105, v105, v105 row_bcast:15 row_mask:0xa bank_mask:0xf
	s_nop 0
	v_add_f32_dpp v104, v104, v104 row_bcast:31 row_mask:0xc bank_mask:0xf
	v_add_f32_dpp v105, v105, v105 row_bcast:31 row_mask:0xc bank_mask:0xf
	s_nop 0
	v_readlane_b32 s98, v105, 63
	s_nop 1
	v_sub_f32_e32 v107, s98, v105
	v_add_f32_e32 v106, v107, v106
	v_fma_f32 v107, -v182, v142, v106
	v_mov_b32_e32 v105, v104
	v_fma_f32 v104, -v178, v141, v105
	ds_write2st64_b64 v108, v[104:105], v[106:107] offset1:1
	ds_write2st64_b64 v108, v[140:141], v[142:143] offset0:2 offset1:3
